# rwkv_apply consumer: LDS operand reads of the next chunk and the bf16 packs interleaved between the MFMAs
# speedup vs baseline: 1.0063x; 1.0023x over previous
.LBB0_1020:
	s_and_b64 vcc, exec, s[0:1]
	s_cbranch_vccz .LBB0_1045
	s_ashr_i32 s4, s2, 4
	s_lshl_b32 s0, s2, 6
	s_ashr_i32 s5, s4, 31
	s_and_b32 s3, s0, 0x3c0
	s_cmpk_lt_u32 s33, 0x100
	s_mov_b64 s[0:1], -1
	s_cbranch_scc0 .LBB0_1025
	s_lshl_b32 s17, s57, 4
	v_or_b32_e32 v0, s3, v133
	v_or_b32_e32 v0, s17, v0
	v_mov_b32_e32 v2, 0
	v_lshlrev_b32_e32 v0, 2, v0
	v_mov_b32_e32 v1, v2
	v_lshl_add_u64 v[0:1], s[40:41], 0, v[0:1]
	v_add_co_u32_e32 v0, vcc, 0x2000, v0
	s_and_b32 s18, s2, 15
	s_nop 0
	v_addc_co_u32_e32 v1, vcc, 0, v1, vcc
	global_load_dword v76, v[0:1], off
	s_lshr_b32 s19, s33, 1
	s_lshl_b64 s[0:1], s[4:5], 23
	s_lshl_b32 s18, s18, 7
	s_and_b32 s19, s19, 0x7fffffe0
	s_add_u32 s18, s19, s18
	s_addc_u32 s19, 0, 0
	v_lshlrev_b32_e32 v0, 5, v146
	v_and_b32_e32 v1, 48, v144
	s_add_u32 s0, s18, s0
	s_waitcnt vmcnt(12)
	v_and_b32_e32 v85, 0x600, v0
	v_lshlrev_b32_e32 v0, 9, v1
	v_mov_b32_e32 v1, v2
	s_addc_u32 s1, s19, s1
	s_waitcnt lgkmcnt(0)
	s_barrier
	v_lshl_add_u64 v[0:1], s[0:1], 0, v[0:1]
	v_lshl_or_b32 v0, v133, 1, v0
	s_mov_b32 s8, 0
	s_waitcnt vmcnt(1)
	v_lshlrev_b32_e32 v82, 4, v146
	v_lshlrev_b32_e32 v83, 3, v146
	v_cmp_gt_u32_e32 vcc, 16, v146
	s_mov_b64 s[6:7], 0
	v_lshlrev_b32_e32 v84, 1, v133
	s_movk_i32 s5, 0x7fff
	s_brev_b32 s9, 16
	s_mov_b32 s10, 0x8001000
	s_mov_b32 s11, 0x8008000
	s_mov_b32 s12, 0x8009000
	s_mov_b32 s13, 0x8010000
	s_mov_b32 s14, 0x8011000
	s_mov_b32 s15, 0x8018000
	s_mov_b32 s16, 0x8019000
	v_mov_b32_e32 v44, v2
	v_mov_b32_e32 v45, v2
	v_mov_b32_e32 v46, v2
	v_mov_b32_e32 v47, v2
	v_mov_b32_e32 v48, v2
	v_mov_b32_e32 v49, v2
	v_mov_b32_e32 v50, v2
	v_mov_b32_e32 v51, v2
	v_mov_b32_e32 v28, v2
	v_mov_b32_e32 v29, v2
	v_mov_b32_e32 v30, v2
	v_mov_b32_e32 v31, v2
	v_mov_b32_e32 v36, v2
	v_mov_b32_e32 v37, v2
	v_mov_b32_e32 v38, v2
	s_lshl_b32 s17, s17, 1
	v_lshl_add_u64 v[78:79], s[52:53], 0, v[0:1]
	v_mov_b32_e32 v39, v2
	s_waitcnt vmcnt(0)
	v_mov_b32_e32 v77, v76
	v_lshlrev_b32_e32 v150, 4, v146
	v_lshlrev_b32_e32 v151, 3, v146
	v_lshrrev_b32_e32 v216, 4, v146
	v_and_b32_e32 v217, 15, v146
	s_lshl_b32 s12, s57, 5
	v_lshlrev_b32_e32 v152, 9, v216
	v_lshl_add_u32 v152, v217, 1, v152
	v_add_u32_e32 v152, s12, v152
	s_lshr_b32 s12, s2, 4
	s_lshl_b32 s12, s12, 22
	s_and_b32 s13, s2, 15
	s_lshl_b32 s13, s13, 6
	s_add_u32 s12, s12, s13
	s_lshl_b32 s13, s57, 4
	s_add_u32 s12, s12, s13
	v_lshl_add_u32 v153, v216, 12, v217
	v_add_u32_e32 v153, s12, v153
	v_lshlrev_b32_e32 v153, 1, v153
	s_add_u32 s6, s52, 0x8000000
	s_addc_u32 s7, s53, 0
	v_mov_b32_e32 v46, 0
	v_mov_b32_e32 v47, 0
	v_mov_b32_e32 v50, 0
	v_mov_b32_e32 v51, 0
	v_mov_b32_e32 v54, 0
	v_mov_b32_e32 v55, 0
	v_mov_b32_e32 v58, 0
	v_mov_b32_e32 v59, 0
	v_mov_b32_e32 v62, 0
	v_mov_b32_e32 v63, 0
	v_mov_b32_e32 v64, 0
	v_mov_b32_e32 v65, 0
	v_mov_b32_e32 v66, 0
	v_mov_b32_e32 v67, 0
	v_mov_b32_e32 v68, 0
	v_mov_b32_e32 v122, 0
	v_mov_b32_e32 v123, 0
	v_mov_b32_e32 v126, 0
	v_mov_b32_e32 v127, 0
	v_mov_b32_e32 v130, 0
	v_mov_b32_e32 v131, 0
	v_mov_b32_e32 v142, 0
	v_mov_b32_e32 v143, 0
	v_mov_b32_e32 v158, 0
	v_mov_b32_e32 v159, 0
	v_mov_b32_e32 v160, 0
	v_mov_b32_e32 v161, 0
	v_mov_b32_e32 v162, 0
	v_mov_b32_e32 v163, 0
	v_mov_b32_e32 v164, 0
	v_mov_b32_e32 v214, 0
	v_mov_b32_e32 v215, 0
	v_mov_b32_e32 v204, 0
	v_mov_b32_e32 v205, 0
	v_mov_b32_e32 v206, 0
	v_mov_b32_e32 v207, 0
	v_mov_b32_e32 v208, 0
	v_mov_b32_e32 v209, 0
	v_mov_b32_e32 v210, 0
	v_mov_b32_e32 v211, 0
	s_mov_b32 s4, 0
	s_lshr_b32 s5, s4, 1
	s_and_b32 s5, s5, 3
	s_mul_i32 s5, s5, 29952
	s_and_b32 s12, s4, 1
	s_mul_i32 s12, s12, 14976
	s_add_u32 s5, s5, s12
	v_add_u32_e32 v149, s5, v152
	v_add_u32_e32 v148, s5, v151
	v_add_u32_e32 v147, s5, v150
	ds_read_u16_d16_hi v64, v149 offset:12800
	ds_read_u16_d16_hi v65, v149 offset:12928
	ds_read_u16_d16_hi v66, v149 offset:13056
	ds_read_u16_d16_hi v67, v149 offset:13184
	ds_read_u16_d16_hi v68, v149 offset:13312
	ds_read_b64 v[60:61], v148 offset:12288
	ds_read_b64 v[44:45], v148 offset:8192
	ds_read_b64 v[48:49], v148 offset:8704
	ds_read_b64 v[52:53], v148 offset:9216
	ds_read_b64 v[56:57], v148 offset:9728
	ds_read_b128 v[36:39], v147 offset:10240
	ds_read_b128 v[40:43], v147 offset:11264
	ds_read_b128 v[4:7], v147 offset:0
	ds_read_b128 v[8:11], v147 offset:1024
	ds_read_b128 v[12:15], v147 offset:2048
	ds_read_b128 v[16:19], v147 offset:3072
	ds_read_b128 v[20:23], v147 offset:4096
	ds_read_b128 v[24:27], v147 offset:5120
	ds_read_b128 v[28:31], v147 offset:6144
	ds_read_b128 v[32:35], v147 offset:7168
	s_waitcnt lgkmcnt(0)
	s_mov_b64 exec, 0xffff
	v_mov_b32_e32 v64, 0
	s_mov_b64 exec, -1
	v_sub_f32_e32 v216, v64, v65
	v_sub_f32_e32 v217, v65, v66
	v_sub_f32_e32 v218, v66, v67
	v_sub_f32_e32 v219, v67, v68
	v_fma_f32 v216, v76, v216, v65
	v_fma_f32 v217, v76, v217, v66
	v_fma_f32 v218, v76, v218, v67
	v_fma_f32 v219, v76, v219, v68
	v_cvt_pk_bf16_f32 v212, v216, v217
	v_cvt_pk_bf16_f32 v213, v218, v219
	s_nop 1
	v_mfma_f32_16x16x32_bf16 v[200:203], v[60:63], v[212:215], 0
	v_mfma_f32_16x16x32_bf16 v[168:171], v[44:47], v[212:215], 0
	v_mfma_f32_16x16x32_bf16 v[172:175], v[48:51], v[212:215], 0
	v_mfma_f32_16x16x32_bf16 v[176:179], v[52:55], v[212:215], 0
	v_mfma_f32_16x16x32_bf16 v[180:183], v[56:59], v[212:215], 0
.Lapc_loop:
	s_add_u32 s13, s4, 1
	s_lshr_b32 s5, s13, 1
	s_and_b32 s5, s5, 3
	s_mul_i32 s5, s5, 29952
	s_and_b32 s12, s13, 1
	s_mul_i32 s12, s12, 14976
	s_add_u32 s5, s5, s12
	v_add_u32_e32 v149, s5, v152
	v_add_u32_e32 v148, s5, v151
	v_add_u32_e32 v147, s5, v150
	v_mfma_f32_16x16x32_bf16 v[200:203], v[36:39], v[204:207], v[200:203]
	ds_read_u16_d16_hi v160, v149 offset:12800
	ds_read_u16_d16_hi v161, v149 offset:12928
	v_mfma_f32_16x16x32_bf16 v[168:171], v[4:7], v[204:207], v[168:171]
	ds_read_u16_d16_hi v162, v149 offset:13056
	ds_read_u16_d16_hi v163, v149 offset:13184
	v_mfma_f32_16x16x32_bf16 v[172:175], v[12:15], v[204:207], v[172:175]
	ds_read_u16_d16_hi v164, v149 offset:13312
	ds_read_b64 v[156:157], v148 offset:12288
	v_mfma_f32_16x16x32_bf16 v[176:179], v[20:23], v[204:207], v[176:179]
	ds_read_b64 v[120:121], v148 offset:8192
	ds_read_b64 v[124:125], v148 offset:8704
	v_mfma_f32_16x16x32_bf16 v[180:183], v[28:31], v[204:207], v[180:183]
	ds_read_b64 v[128:129], v148 offset:9216
	ds_read_b64 v[140:141], v148 offset:9728
	v_mfma_f32_16x16x32_bf16 v[200:203], v[40:43], v[208:211], v[200:203]
	ds_read_b128 v[112:115], v147 offset:10240
	ds_read_b128 v[116:119], v147 offset:11264
	v_mfma_f32_16x16x32_bf16 v[168:171], v[8:11], v[208:211], v[168:171]
	ds_read_b128 v[80:83], v147 offset:0
	ds_read_b128 v[84:87], v147 offset:1024
	v_mfma_f32_16x16x32_bf16 v[172:175], v[16:19], v[208:211], v[172:175]
	ds_read_b128 v[88:91], v147 offset:2048
	ds_read_b128 v[92:95], v147 offset:3072
	v_mfma_f32_16x16x32_bf16 v[176:179], v[24:27], v[208:211], v[176:179]
	ds_read_b128 v[96:99], v147 offset:4096
	ds_read_b128 v[100:103], v147 offset:5120
	v_mfma_f32_16x16x32_bf16 v[180:183], v[32:35], v[208:211], v[180:183]
	ds_read_b128 v[104:107], v147 offset:6144
	ds_read_b128 v[108:111], v147 offset:7168
	s_waitcnt lgkmcnt(15)
	v_sub_f32_e32 v216, v160, v161
	v_sub_f32_e32 v217, v161, v162
	v_sub_f32_e32 v218, v162, v163
	v_sub_f32_e32 v219, v163, v164
	v_fma_f32 v216, v76, v216, v161
	v_fma_f32 v217, v76, v217, v162
	v_fma_f32 v218, v76, v218, v163
	v_fma_f32 v219, v76, v219, v164
	v_cvt_pk_bf16_f32 v212, v216, v217
	v_cvt_pk_bf16_f32 v213, v218, v219
	s_waitcnt lgkmcnt(10)
	s_nop 1
	v_mfma_f32_16x16x32_bf16 v[224:227], v[156:159], v[212:215], 0
	v_cvt_pk_bf16_f32 v220, v200, v201
	v_cvt_pk_bf16_f32 v221, v202, v203
	v_mfma_f32_16x16x32_bf16 v[184:187], v[120:123], v[212:215], 0
	v_cvt_pk_bf16_f32 v204, v168, v169
	v_cvt_pk_bf16_f32 v205, v170, v171
	v_mfma_f32_16x16x32_bf16 v[188:191], v[124:127], v[212:215], 0
	v_cvt_pk_bf16_f32 v206, v172, v173
	v_cvt_pk_bf16_f32 v207, v174, v175
	v_mfma_f32_16x16x32_bf16 v[192:195], v[128:131], v[212:215], 0
	v_cvt_pk_bf16_f32 v208, v176, v177
	v_cvt_pk_bf16_f32 v209, v178, v179
	v_mfma_f32_16x16x32_bf16 v[196:199], v[140:143], v[212:215], 0
	v_cvt_pk_bf16_f32 v210, v180, v181
	v_cvt_pk_bf16_f32 v211, v182, v183
	s_lshl_b32 s12, s4, 15
	s_add_u32 s8, s6, s12
	s_addc_u32 s9, s7, 0
	s_add_u32 s10, s8, 0x1000
	s_addc_u32 s11, s9, 0
	global_store_short v153, v220, s[8:9]
	global_store_short_d16_hi v153, v220, s[8:9] offset:2048
	global_store_short v153, v221, s[10:11]
	global_store_short_d16_hi v153, v221, s[10:11] offset:2048
	s_waitcnt lgkmcnt(0)
	s_barrier
	s_add_u32 s4, s4, 2
	s_cmp_lt_u32 s4, 256
	s_cbranch_scc0 .Lapc_last
	s_lshr_b32 s5, s4, 1
	s_and_b32 s5, s5, 3
	s_mul_i32 s5, s5, 29952
	s_and_b32 s12, s4, 1
	s_mul_i32 s12, s12, 14976
	s_add_u32 s5, s5, s12
	v_add_u32_e32 v149, s5, v152
	v_add_u32_e32 v148, s5, v151
	v_add_u32_e32 v147, s5, v150
	v_mfma_f32_16x16x32_bf16 v[224:227], v[112:115], v[204:207], v[224:227]
	ds_read_u16_d16_hi v64, v149 offset:12800
	ds_read_u16_d16_hi v65, v149 offset:12928
	v_mfma_f32_16x16x32_bf16 v[184:187], v[80:83], v[204:207], v[184:187]
	ds_read_u16_d16_hi v66, v149 offset:13056
	ds_read_u16_d16_hi v67, v149 offset:13184
	v_mfma_f32_16x16x32_bf16 v[188:191], v[88:91], v[204:207], v[188:191]
	ds_read_u16_d16_hi v68, v149 offset:13312
	ds_read_b64 v[60:61], v148 offset:12288
	v_mfma_f32_16x16x32_bf16 v[192:195], v[96:99], v[204:207], v[192:195]
	ds_read_b64 v[44:45], v148 offset:8192
	ds_read_b64 v[48:49], v148 offset:8704
	v_mfma_f32_16x16x32_bf16 v[196:199], v[104:107], v[204:207], v[196:199]
	ds_read_b64 v[52:53], v148 offset:9216
	ds_read_b64 v[56:57], v148 offset:9728
	v_mfma_f32_16x16x32_bf16 v[224:227], v[116:119], v[208:211], v[224:227]
	ds_read_b128 v[36:39], v147 offset:10240
	ds_read_b128 v[40:43], v147 offset:11264
	v_mfma_f32_16x16x32_bf16 v[184:187], v[84:87], v[208:211], v[184:187]
	ds_read_b128 v[4:7], v147 offset:0
	ds_read_b128 v[8:11], v147 offset:1024
	v_mfma_f32_16x16x32_bf16 v[188:191], v[92:95], v[208:211], v[188:191]
	ds_read_b128 v[12:15], v147 offset:2048
	ds_read_b128 v[16:19], v147 offset:3072
	v_mfma_f32_16x16x32_bf16 v[192:195], v[100:103], v[208:211], v[192:195]
	ds_read_b128 v[20:23], v147 offset:4096
	ds_read_b128 v[24:27], v147 offset:5120
	v_mfma_f32_16x16x32_bf16 v[196:199], v[108:111], v[208:211], v[196:199]
	ds_read_b128 v[28:31], v147 offset:6144
	ds_read_b128 v[32:35], v147 offset:7168
	s_waitcnt lgkmcnt(15)
	v_sub_f32_e32 v216, v64, v65
	v_sub_f32_e32 v217, v65, v66
	v_sub_f32_e32 v218, v66, v67
	v_sub_f32_e32 v219, v67, v68
	v_fma_f32 v216, v76, v216, v65
	v_fma_f32 v217, v76, v217, v66
	v_fma_f32 v218, v76, v218, v67
	v_fma_f32 v219, v76, v219, v68
	v_cvt_pk_bf16_f32 v212, v216, v217
	v_cvt_pk_bf16_f32 v213, v218, v219
	s_waitcnt lgkmcnt(10)
	s_nop 1
	v_mfma_f32_16x16x32_bf16 v[200:203], v[60:63], v[212:215], 0
	v_cvt_pk_bf16_f32 v220, v224, v225
	v_cvt_pk_bf16_f32 v221, v226, v227
	v_mfma_f32_16x16x32_bf16 v[168:171], v[44:47], v[212:215], 0
	v_cvt_pk_bf16_f32 v204, v184, v185
	v_cvt_pk_bf16_f32 v205, v186, v187
	v_mfma_f32_16x16x32_bf16 v[172:175], v[48:51], v[212:215], 0
	v_cvt_pk_bf16_f32 v206, v188, v189
	v_cvt_pk_bf16_f32 v207, v190, v191
	v_mfma_f32_16x16x32_bf16 v[176:179], v[52:55], v[212:215], 0
	v_cvt_pk_bf16_f32 v208, v192, v193
	v_cvt_pk_bf16_f32 v209, v194, v195
	v_mfma_f32_16x16x32_bf16 v[180:183], v[56:59], v[212:215], 0
	v_cvt_pk_bf16_f32 v210, v196, v197
	v_cvt_pk_bf16_f32 v211, v198, v199
	s_lshl_b32 s12, s13, 15
	s_add_u32 s8, s6, s12
	s_addc_u32 s9, s7, 0
	s_add_u32 s10, s8, 0x1000
	s_addc_u32 s11, s9, 0
	global_store_short v153, v220, s[8:9]
	global_store_short_d16_hi v153, v220, s[8:9] offset:2048
	global_store_short v153, v221, s[10:11]
	global_store_short_d16_hi v153, v221, s[10:11] offset:2048
	s_waitcnt lgkmcnt(0)
	s_branch .Lapc_loop
.Lapc_last:
	v_mfma_f32_16x16x32_bf16 v[224:227], v[112:115], v[204:207], v[224:227]
	v_mfma_f32_16x16x32_bf16 v[184:187], v[80:83], v[204:207], v[184:187]
	v_mfma_f32_16x16x32_bf16 v[188:191], v[88:91], v[204:207], v[188:191]
	v_mfma_f32_16x16x32_bf16 v[192:195], v[96:99], v[204:207], v[192:195]
	v_mfma_f32_16x16x32_bf16 v[196:199], v[104:107], v[204:207], v[196:199]
	v_mfma_f32_16x16x32_bf16 v[224:227], v[116:119], v[208:211], v[224:227]
	v_mfma_f32_16x16x32_bf16 v[184:187], v[84:87], v[208:211], v[184:187]
	v_mfma_f32_16x16x32_bf16 v[188:191], v[92:95], v[208:211], v[188:191]
	v_mfma_f32_16x16x32_bf16 v[192:195], v[100:103], v[208:211], v[192:195]
	v_mfma_f32_16x16x32_bf16 v[196:199], v[108:111], v[208:211], v[196:199]
	s_nop 15
	v_cvt_pk_bf16_f32 v220, v224, v225
	v_cvt_pk_bf16_f32 v221, v226, v227
	s_lshl_b32 s12, s13, 15
	s_add_u32 s8, s6, s12
	s_addc_u32 s9, s7, 0
	s_add_u32 s10, s8, 0x1000
	s_addc_u32 s11, s9, 0
	global_store_short v153, v220, s[8:9]
	global_store_short_d16_hi v153, v220, s[8:9] offset:2048
	global_store_short v153, v221, s[10:11]
	global_store_short_d16_hi v153, v221, s[10:11] offset:2048
	s_waitcnt lgkmcnt(0)
